# grid barrier: the L1 invalidate issued and waited for by a wave that does not run the protocol (wave 4 / wave 1), off wave 0's arrive chain
# baseline (speedup 1.0000x reference)
;     __device__ __forceinline__ bool next(int i, Unit& o) const { if (i) return false; o = u; return true; }
;     __host__ __device__ bool next(int i, Unit& u) const {
;         const long L = (long)i * G + c; if (L >= nwg) return false;
;         int wgid = (int)L; { const int q = nwg / NXCD, r = nwg % NXCD, xcd = wgid % NXCD, off = wgid / NXCD; wgid = (xcd < r ? xcd * (q + 1) : r * (q + 1) + (xcd - r) * q) + off; }
;         const int nig = wgm * nN, gid = wgid / nig, fm = gid * wgm, gsz = (nM - fm) < wgm ? (nM - fm) : wgm;
;         u.pm = fm + ((wgid % nig) % gsz); u.pn = (wgid % nig) / gsz; return true;
; __device__ __forceinline__ void xcd_barrier(const XcdBarrier& b, const int wave) {
;     ...
;         }
;     }
;     __syncthreads();
.LBB0_163:
	s_cmp_eq_u32 s48, 64
	s_cbranch_scc0 mk_winv_p0
	buffer_inv sc1
	s_waitcnt vmcnt(0)
mk_winv_p0:
	s_mov_b32 s4, -1
	s_waitcnt lgkmcnt(0)
	s_barrier
	s_cmpk_lt_i32 s2, 0x400
	v_mbcnt_lo_u32_b32 v0, s4, 0
	v_mbcnt_hi_u32_b32 v8, s4, v0
	s_cselect_b64 s[8:9], -1, 0
	s_cmpk_gt_i32 s2, 0x3ff
	s_cbranch_scc1 .LBB0_169
	s_ashr_i32 s4, s2, 31
	s_lshr_b32 s4, s4, 29
	s_add_i32 s6, s2, s4
	s_and_b32 s4, s6, -8
	s_sub_i32 s7, s2, s4
	s_cmp_gt_i32 s7, -1
	s_cbranch_scc0 .LBB0_166
	s_lshl_b32 s10, s7, 7
	s_cbranch_execz .LBB0_167
	s_branch .LBB0_168

;     __device__ __forceinline__ bool next(int i, Unit& o) const { if (i) return false; o = u; return true; }
; __device__ __forceinline__ void xcd_barrier(const XcdBarrier& b, const int wave) {
;     ...
;         }
;     }
;     __syncthreads();
; __global__ void __launch_bounds__(NWAVES * 64, 2) mk_fwd(Args args) {
;     ...
;         pg8::AddrF1u g{abt, qkv + (size_t)3 * T * 1024}; pg8::StaticOrder S; S.init(2048, T, G, (int)blockIdx.x, WGM_F);
;         pg8::EpiDft1 E{zt, lds};
;         const int nu = (S.nwg - (int)blockIdx.x + G - 1) / G;
; #pragma unroll 1
;         for (int i = 0; i < nu; ++i) { pg8::OneUnit o; (void)S.next(i, o.u);
;             pg8::gemm_phase<pg8::EpiDft1, pg8::OneUnit, pg8::AddrF1u, true>(lds, 256, g, o, E, wave); }
.LBB0_339:
	s_cmp_eq_u32 s48, 64
	s_cbranch_scc0 mk_winv_p1
	s_cmp_eq_u32 s50, 0
	s_cbranch_scc0 mk_winv_p1
	buffer_inv sc1
	s_waitcnt vmcnt(0)
mk_winv_p1:
	s_add_u32 s68, s94, 0x14400000
	s_addc_u32 s69, s95, 0
	s_abs_i32 s0, s3
	s_waitcnt lgkmcnt(0)
	v_cvt_f32_u32_e32 v0, s0
	s_sub_i32 s1, s3, s2
	s_add_i32 s4, s1, 0x1ff
	s_sub_i32 s1, 0xfffffe01, s1
	v_rcp_iflag_f32_e32 v0, v0
	s_xor_b32 s5, s4, s3
	s_max_i32 s1, s4, s1
	s_sub_i32 s4, 0, s0
	v_mul_f32_e32 v0, 0x4f7ffffe, v0
	v_cvt_u32_f32_e32 v0, v0
	s_ashr_i32 s5, s5, 31
	s_barrier
	v_readfirstlane_b32 s6, v0
	s_mul_i32 s4, s4, s6
	s_mul_hi_u32 s4, s6, s4
	s_add_i32 s6, s6, s4
	s_mul_hi_u32 s4, s1, s6
	s_mul_i32 s6, s4, s0
	s_sub_i32 s1, s1, s6
	s_add_i32 s6, s4, 1
	s_sub_i32 s7, s1, s0
	s_cmp_ge_u32 s1, s0
	s_cselect_b32 s4, s6, s4
	s_cselect_b32 s1, s7, s1
	s_add_i32 s6, s4, 1
	s_cmp_ge_u32 s1, s0
	s_cselect_b32 s0, s6, s4
	s_xor_b32 s0, s0, s5
	s_sub_i32 s14, s0, s5
	s_cmp_lt_i32 s14, 1
	s_mov_b32 s0, 0
	s_cbranch_scc1 .LBB0_356
	v_readlane_b32 s6, v254, 14
	s_bfe_u32 s1, s6, 0x20006
	s_ashr_i32 s15, s3, 31
	s_ashr_i32 s38, s2, 31
	s_lshl_b32 s39, s1, 12
	v_readlane_b32 s11, v254, 16
	s_cmp_eq_u32 s11, 1
	s_cselect_b64 s[4:5], -1, 0
	s_cmpk_lt_u32 s6, 0x100
	s_cselect_b64 s[6:7], -1, 0
	s_lshl_b32 s8, s11, 15
	s_add_i32 s41, s8, 0
	s_lshl_b32 s8, s11, 7
	s_lshl_b32 s9, s1, 5
	s_lshl_b32 s40, s1, 2
	s_lshl_b32 s10, s1, 4
	s_or_b32 s46, s8, s9
	s_lshl_b32 s8, s11, 16
	s_lshl_b32 s1, s1, 14
	s_add_i32 s42, s41, 0x10000
	s_add_i32 s43, s41, 0x12000
	s_add_i32 s44, s41, 0x14000
	s_add_i32 s45, s41, 0x16000
	s_or_b32 s47, s8, s1
	s_add_u32 s8, s94, 0x1840c000
	s_addc_u32 s9, s95, 0
	s_add_i32 s52, s48, s10
	v_mov_b64_e32 v[128:129], 0x1ff
	s_mov_b32 s53, 0x1ffffe0
	v_mov_b32_e32 v131, 0
	s_mov_b64 s[10:11], 0x80
	s_mov_b32 s54, 0x5040100
	v_mov_b32_e32 v140, 1
	s_mov_b32 s55, 0

; __device__ __forceinline__ unsigned lane_id_fresh() { unsigned m = ~0u; asm volatile("" : "+s"(m)); return __builtin_amdgcn_mbcnt_hi(m, __builtin_amdgcn_mbcnt_lo(m, 0u)); }
; #define GAS __attribute__((address_space(1)))
; #define LAS __attribute__((address_space(3)))
; __device__ __forceinline__ void at_dma_v(LAS unsigned char* vdst, const bf16_t* vbase, int tq0, int dil, int tile, int lane_) { at_dma_k(vdst, vbase, tq0, dil, tile, lane_); }
; __device__ __forceinline__ void at_load_q(bf16x8 (&qr)[8], const bf16_t* qb, int tq0, int dil, int lane) {
;     const bf16_t* qrow = qb + (size_t)(tq0 + dil * (lane & 31)) * 128 + (lane >> 5) * 8;
; #pragma unroll
;     for (int s = 0; s < 8; ++s) qr[s] = *(const GAS bf16x8*)(qrow + 16 * s);
; }
; __device__ __forceinline__ void at_unit_prologue(LAS unsigned char* wl, bf16x8 (&qr)[8], const bf16_t* qb, const bf16_t* kb, const bf16_t* vb, int tq0, int dil, int lane) {
;     at_dma_k(wl, kb, tq0, dil, 0, lane); at_dma_v(wl + 8192, vb, tq0, dil, 0, lane); at_load_q(qr, qb, tq0, dil, lane);
; __global__ void __launch_bounds__(NWAVES * 64, 2) mk_fwd(Args args) {
;     ...
;     {
;         LAS unsigned char* wl = lds + wave * 16384;
;         int lna = (int)lane_id_fresh(); asm volatile("" : "+v"(lna));
;         constexpr int NU = NB * NH * 128;
;     ...
;         int U = vwave;
;         if (U < NU) {
;             const bf16_t *cq, *ck, *cv, *nq, *nk, *nv, *c0, *c1, *n0, *n1; const float *cm0, *cm1, *nm0, *nm1; bf16_t *cy, *ny; int ctq, ntq = 0; float csl, nsl = 0.f;
;             AT_DEC_C(U, cq, ck, cv, ctq, csl, c0, c1, cm0, cm1, cy);
;             nq = cq; nk = ck; nv = cv; n0 = c0; n1 = c1; nm0 = cm0; nm1 = cm1; ny = cy;
;             bf16x8 qr[8];
;             at_unit_prologue(wl, qr, cq, ck, cv, ctq, 1, lna);
.LBB0_471:
	s_cmp_eq_u32 s48, 64
	s_cbranch_scc0 mk_winv_p2a
	s_cmp_eq_u32 s50, 0
	s_cbranch_scc0 mk_winv_p2a
	buffer_inv sc1
	s_waitcnt vmcnt(0)
mk_winv_p2a:
	v_writelane_b32 v254, s94, 28
	s_mov_b32 s4, -1
	s_waitcnt lgkmcnt(0)
	v_writelane_b32 v254, s95, 29
	s_barrier
	v_writelane_b32 v254, s96, 30
	v_mbcnt_lo_u32_b32 v0, s4, 0
	v_mbcnt_hi_u32_b32 v198, s4, v0
	s_cmpk_gt_i32 s86, 0xfff
	v_writelane_b32 v254, s97, 31
	s_cbranch_scc1 .LBB0_518
	v_readlane_b32 s16, v254, 2
	v_readlane_b32 s18, v254, 4
	v_readlane_b32 s19, v254, 5
	s_add_u32 s16, s18, 0x4000000
	s_addc_u32 s52, s19, 0
	s_add_u32 s53, s18, 0x4100000
	s_addc_u32 s87, s19, 0
	s_ashr_i32 s4, s86, 7
	s_and_b32 s12, s4, 7
	s_ashr_i32 s5, s4, 31
	s_ashr_i32 s13, s86, 10
	s_lshl_b32 s15, s12, 7
	s_lshl_b64 s[6:7], s[4:5], 19
	s_lshl_b64 s[8:9], s[4:5], 20
	s_add_u32 s10, s84, s8
	s_addc_u32 s11, s85, s9
	s_add_u32 s88, s94, 0x10400000
	s_addc_u32 s89, s95, 0
	s_add_u32 s60, s88, s6
	s_addc_u32 s61, s89, s7
	s_add_u32 s90, s94, 0x12400000
	s_addc_u32 s91, s95, 0
	s_add_u32 s70, s90, s6
	s_addc_u32 s71, s91, s7
	s_add_i32 s12, s12, 1
	v_cvt_f32_ubyte0_e32 v0, s12
	s_mov_b32 s6, 0x42fc0000
	v_mov_b32_e32 v1, 0x42800000
	v_cmp_lt_f32_e32 vcc, s6, v0
	s_and_b64 s[6:7], vcc, exec
	s_cselect_b32 s6, 0xffffffc0, 0
	v_cndmask_b32_e32 v1, 0, v1, vcc
	v_sub_f32_e32 v0, v1, v0
	v_exp_f32_e32 v0, v0
	s_mov_b32 m0, s83
	v_and_b32_e32 v200, 31, v198
	v_ashrrev_i32_e32 v201, 4, v198
	v_ldexp_f32 v0, v0, s6
	s_lshl_b32 s6, s86, 5
	s_and_b32 s94, s6, 0xfe0
	s_add_u32 s58, s18, s8
	s_addc_u32 s59, s19, s9
	s_add_u32 s56, s0, s8
	s_addc_u32 s57, s1, s9
	s_lshl_b64 s[6:7], s[4:5], 15
	v_mul_f32_e32 v114, 0x3fb8aa3b, v0
	s_add_u32 s4, s16, s6
	v_mov_b32_e32 v0, v198
	s_addc_u32 s5, s52, s7
	s_add_u32 s6, s53, s6
	v_ashrrev_i32_e32 v1, 3, v0
	v_bitop3_b32 v0, v0, v1, 7 bitop3:0x6c
	v_add_u32_e32 v1, s94, v1
	s_addc_u32 s7, s87, s7
	s_mul_hi_i32 s8, s13, 0xc00000
	s_mul_i32 s13, s13, 0xc00000
	v_max_i32_e32 v2, 64, v1
	s_add_u32 s9, s68, s13
	v_subrev_u32_e32 v2, 64, v2
	s_addc_u32 s8, s69, s8
	v_lshlrev_b32_e32 v0, 4, v0
	v_min_u32_e32 v2, 0xfff, v2
	s_add_u32 s9, s9, s15
	v_lshl_add_u32 v2, v2, 7, v0
	s_addc_u32 s8, s8, 0
	global_load_lds_dwordx4 v2, s[60:61]
	v_max_i32_e32 v2, 56, v1
	s_add_u32 s54, s9, 0x800
	v_subrev_u32_e32 v2, 56, v2
	s_addc_u32 s55, s8, 0
	v_min_u32_e32 v2, 0xfff, v2
	s_add_i32 s95, s83, 0x400
	v_lshl_add_u32 v2, v2, 7, v0
	s_mov_b32 m0, s95
	s_add_i32 s96, s83, 0x800
	global_load_lds_dwordx4 v2, s[60:61]
	v_max_i32_e32 v2, 48, v1
	v_subrev_u32_e32 v2, 48, v2
	v_max_i32_e32 v1, 40, v1
	v_min_u32_e32 v2, 0xfff, v2
	v_subrev_u32_e32 v1, 40, v1
	v_lshl_add_u32 v2, v2, 7, v0
	s_mov_b32 m0, s96
	v_min_u32_e32 v1, 0xfff, v1
	s_add_i32 s38, s83, 0xc00
	global_load_lds_dwordx4 v2, s[60:61]
	v_lshl_add_u32 v0, v1, 7, v0
	s_mov_b32 m0, s38
	s_add_i32 s39, s83, 0x2000
	global_load_lds_dwordx4 v0, s[60:61]
	v_mov_b32_e32 v0, v198
	s_mov_b32 m0, s39
	v_ashrrev_i32_e32 v1, 3, v0
	v_bitop3_b32 v0, v0, v1, 7 bitop3:0x6c
	v_add_u32_e32 v1, s94, v1
	v_max_i32_e32 v2, 64, v1
	v_subrev_u32_e32 v2, 64, v2
	v_lshlrev_b32_e32 v0, 4, v0
	v_min_u32_e32 v2, 0xfff, v2
	v_lshl_add_u32 v2, v2, 7, v0
	global_load_lds_dwordx4 v2, s[70:71]
	v_max_i32_e32 v2, 56, v1
	v_subrev_u32_e32 v2, 56, v2
	v_min_u32_e32 v2, 0xfff, v2
	s_add_i32 s67, s83, 0x2400
	v_lshl_add_u32 v2, v2, 7, v0
	s_mov_b32 m0, s67
	s_add_i32 s82, s83, 0x2800
	global_load_lds_dwordx4 v2, s[70:71]
	v_max_i32_e32 v2, 48, v1
	v_subrev_u32_e32 v2, 48, v2
	v_max_i32_e32 v1, 40, v1
	v_min_u32_e32 v2, 0xfff, v2
	v_subrev_u32_e32 v1, 40, v1
	v_lshl_add_u32 v2, v2, 7, v0
	s_mov_b32 m0, s82
	v_min_u32_e32 v1, 0xfff, v1
	s_add_i32 s66, s83, 0x2c00
	global_load_lds_dwordx4 v2, s[70:71]
	v_lshl_add_u32 v0, v1, 7, v0
	s_mov_b32 m0, s66
	v_mov_b32_e32 v1, 0
	global_load_lds_dwordx4 v0, s[70:71]
	v_or_b32_e32 v0, s94, v200
	v_lshlrev_b32_e32 v0, 8, v0
	v_lshl_add_u64 v[2:3], s[10:11], 0, v[0:1]
	v_ashrrev_i32_e32 v0, 2, v198
	v_and_b32_e32 v162, -8, v0
	v_ashrrev_i32_e32 v163, 31, v162
	v_lshl_add_u64 v[2:3], v[162:163], 1, v[2:3]
	global_load_dwordx4 v[82:85], v[2:3], off
	global_load_dwordx4 v[86:89], v[2:3], off offset:32
	global_load_dwordx4 v[90:93], v[2:3], off offset:64
	global_load_dwordx4 v[94:97], v[2:3], off offset:96
	global_load_dwordx4 v[98:101], v[2:3], off offset:128
	global_load_dwordx4 v[102:105], v[2:3], off offset:160
	global_load_dwordx4 v[106:109], v[2:3], off offset:192
	global_load_dwordx4 v[110:113], v[2:3], off offset:224
	v_ashrrev_i32_e32 v0, 5, v198
	v_lshlrev_b32_e32 v3, 3, v0
	v_lshlrev_b32_e32 v0, 2, v0
	v_sub_u32_e32 v0, v0, v200
	v_subrev_u32_e32 v202, 64, v0
	v_xor_b32_e32 v0, v201, v198
	v_lshlrev_b32_e32 v0, 3, v0
	v_add_u32_e32 v29, 4, v201
	v_and_b32_e32 v164, 0x78, v0
	v_xor_b32_e32 v0, v29, v198
	v_lshlrev_b32_e32 v0, 3, v0
	v_add_u32_e32 v199, 8, v201
	v_and_b32_e32 v166, 0x78, v0
	v_xor_b32_e32 v0, v199, v198
	v_lshlrev_b32_e32 v0, 3, v0
; #define GAS __attribute__((address_space(1)))
; __device__ __forceinline__ void attn_unit(const bool FINAL, const bool HN, LAS unsigned char* wl, const bf16_t* qb, const bf16_t* kb, const bf16_t* vb, int tq0, int dil, float sl, bf16x8 (&qr)[8], const bf16_t* nqb, const bf16_t* nkb, const bf16_t* nvb, int ntq0, int ndil, ...
;     const int r32 = lane & 31, hi = lane >> 5;
;     LAS unsigned char* kbuf = wl; LAS unsigned char* vbuf = wl + 8192;
;     const int jlo = 64 - tq0 / dil, jhi = 64 + (SEQ - 1 - tq0) / dil;
;     const float lo_i = (float)max(-64, jlo - 64 - r32), hi_i = (float)min(64, jhi - 64 - r32);
;     const bool interior = (jlo <= 0) && (jhi >= 159);
;     float m_run = -1e30f, l_run = 0.f;
;     f32x16 oT[4];
; #pragma unroll
;     for (int d0 = 0; d0 < 4; ++d0)
; #pragma unroll
;         for (int r = 0; r < 16; ++r) oT[d0][r] = 0.f;
;     asm volatile("s_waitcnt vmcnt(0)" ::: "memory");
; #pragma unroll
;     for (int s = 0; s < 8; ++s) asm volatile("" : "+v"(qr[s]));
;     long q8[8];
; #pragma unroll
;     for (int s = 0; s < 8; ++s) q8[s] = bf16x8_to_fp8(qr[s]);
;     f32x2 st1 = {0.f, 0.f}, st2 = {0.f, 0.f};
;     if (FINAL) { const size_t tqs = (size_t)(tq0 + dil * r32) * 2; st1 = *(const GAS f32x2*)(ml0 + tqs); st2 = *(const GAS f32x2*)(ml1 + tqs); }
;     const int rr0 = lane >> 4, cs = lane & 15;
;     const LAS unsigned char* krd = kbuf + r32 * 128 + hi * 8;
;     const int kx = (r32 & 7) << 4;
;     ...
;         LAS unsigned char* wrow = vbuf + r32 * 256 + hi * 8; const int qx = r32 & 15;
; #pragma unroll
;         for (int d0 = 0; d0 < 4; ++d0)
; #pragma unroll
;             for (int g4 = 0; g4 < 4; ++g4) { u32x2 w; w.x = cvtpk(oT[d0][4 * g4] * osc, oT[d0][4 * g4 + 1] * osc); w.y = cvtpk(oT[d0][4 * g4 + 2] * osc, oT[d0][4 * g4 + 3] * osc);
;                 *(LAS u32x2*)(wrow + (((4 * d0 + g4) ^ qx) << 4)) = w; }
;     }
;     asm volatile("s_waitcnt lgkmcnt(0)" ::: "memory"); SBAR();
;     if (!FINAL) {
; #pragma unroll
;         for (int i = 0; i < 8; ++i) a0[i] = *(const LAS v4u*)(vbuf + (4 * i + rr0) * 256 + cs * 16);
; #pragma unroll
;         for (int i = 0; i < 8; ++i) { const int row = 4 * i + rr0, c = cs ^ (row & 15);
;             *(GAS v4u*)(part + (size_t)(tq0 + dil * row) * 128 + 8 * c) = a0[i]; }
;     } else {
; #pragma unroll
;         for (int i = 0; i < 8; ++i) { const int row = 4 * i + rr0, c = cs ^ (row & 15);
	v_add_u32_e32 v203, 12, v201
	v_and_b32_e32 v168, 0x78, v0
	v_xor_b32_e32 v0, v203, v198
	v_lshlrev_b32_e32 v0, 3, v0
	v_add_u32_e32 v37, 20, v201
	v_and_b32_e32 v170, 0x78, v0
	v_xor_b32_e32 v0, v37, v198
	v_lshlrev_b32_e32 v0, 3, v0
	v_add_u32_e32 v208, 24, v201
	v_and_b32_e32 v172, 0x78, v0
	v_xor_b32_e32 v0, v208, v198
	v_lshlrev_b32_e32 v0, 3, v0
	v_add_u32_e32 v209, 28, v201
	v_and_b32_e32 v174, 0x78, v0
	v_xor_b32_e32 v0, v209, v198
	v_lshlrev_b32_e32 v0, 3, v0
	v_and_b32_e32 v176, 0x78, v0
	v_lshlrev_b32_e32 v0, 8, v200
	v_lshlrev_b32_e32 v4, 4, v198
	s_movk_i32 s8, 0x70
	v_add3_u32 v210, s83, v0, v3
	v_mov_b32_e32 v0, 0xf0
	v_bitop3_b32 v12, v4, s8, v4 bitop3:0xc
	v_bitop3_b32 v18, v4, s8, v0 bitop3:0x6c
	s_movk_i32 s8, 0x80
	v_bitop3_b32 v19, v4, s8, v0 bitop3:0x6c
	s_movk_i32 s8, 0x90
	v_bitop3_b32 v20, v4, s8, v0 bitop3:0x6c
	s_movk_i32 s8, 0xa0
	v_bitop3_b32 v21, v4, s8, v0 bitop3:0x6c
	s_movk_i32 s8, 0xb0
	v_bitop3_b32 v22, v4, s8, v0 bitop3:0x6c
	s_movk_i32 s8, 0xc0
	v_bitop3_b32 v23, v4, s8, v0 bitop3:0x6c
	s_movk_i32 s8, 0xd0
	v_lshlrev_b32_e32 v2, 7, v200
	s_movk_i32 s9, 0x50
	s_movk_i32 s12, 0x60
	v_bitop3_b32 v24, v4, s8, v0 bitop3:0x6c
	s_movk_i32 s8, 0xe0
	v_add3_u32 v2, s83, v2, v3
	v_bitop3_b32 v3, v4, 16, v0 bitop3:0x6c
	v_bitop3_b32 v13, v4, 32, v0 bitop3:0x6c
	v_bitop3_b32 v14, v4, 48, v0 bitop3:0x6c
	v_bitop3_b32 v15, v4, 64, v0 bitop3:0x6c
	v_bitop3_b32 v16, v4, s9, v0 bitop3:0x6c
	v_bitop3_b32 v17, v4, s12, v0 bitop3:0x6c
	v_bitop3_b32 v0, v4, s8, v0 bitop3:0x6c
	v_mov_b32_e32 v6, 0x70
	v_add_u32_e32 v234, v210, v0
	v_mbcnt_hi_u32_b32 v0, -1, v253
	v_and_b32_e32 v5, 0x70, v4
	v_bitop3_b32 v7, v4, 16, v6 bitop3:0x6c
	v_bitop3_b32 v8, v4, 32, v6 bitop3:0x6c
	v_bitop3_b32 v9, v4, 48, v6 bitop3:0x6c
	v_bitop3_b32 v10, v4, 64, v6 bitop3:0x6c
	v_bitop3_b32 v11, v4, s9, v6 bitop3:0x6c
	v_bitop3_b32 v6, v4, s12, v6 bitop3:0x6c
	v_and_b32_e32 v26, 63, v201
	v_and_b32_e32 v0, 64, v0
	v_and_b32_e32 v28, 63, v29
	v_add_u32_e32 v212, v2, v5
	v_add_u32_e32 v213, v2, v7
	v_add_u32_e32 v215, v2, v8
	v_add_u32_e32 v216, v2, v9
	v_add_u32_e32 v217, v2, v10
	v_add_u32_e32 v218, v2, v11
	v_add_u32_e32 v219, v2, v6
	v_add_u32_e32 v220, v2, v12
	v_or_b32_e32 v2, v0, v26
	v_and_b32_e32 v30, 63, v199
	v_lshlrev_b32_e32 v246, 2, v2
	v_or_b32_e32 v2, v0, v28
	v_add_u32_e32 v35, 16, v201
	v_and_b32_e32 v32, 63, v203
	v_lshlrev_b32_e32 v247, 2, v2
	v_or_b32_e32 v2, v0, v30
	v_and_b32_e32 v34, 63, v35
	v_lshlrev_b32_e32 v248, 2, v2
	v_or_b32_e32 v2, v0, v32
	v_and_b32_e32 v36, 63, v37
	v_lshlrev_b32_e32 v249, 2, v2
	v_or_b32_e32 v2, v0, v34
	v_readlane_b32 s17, v254, 3
	s_movk_i32 s13, 0xf0
	v_and_b32_e32 v211, 0xf0, v4
	v_and_b32_e32 v38, 63, v208
	v_and_b32_e32 v40, 63, v209
	v_lshlrev_b32_e32 v250, 2, v2
	v_or_b32_e32 v2, v0, v36
	v_writelane_b32 v254, s16, 32
	v_bitop3_b32 v4, v4, s13, v4 bitop3:0xc
	v_add_u32_e32 v25, s83, v211
	v_lshlrev_b32_e32 v27, 8, v201
	v_lshlrev_b32_e32 v29, 8, v29
	v_lshlrev_b32_e32 v31, 8, v199
	v_lshlrev_b32_e32 v33, 8, v203
	v_lshlrev_b32_e32 v35, 8, v35
	v_lshlrev_b32_e32 v37, 8, v37
	v_lshlrev_b32_e32 v39, 8, v208
	v_lshlrev_b32_e32 v41, 8, v209
	s_mov_b32 s12, 0x41200000
	s_mov_b32 s16, 0x41800000
	s_mov_b32 s18, 0x41900000
	s_mov_b32 s20, 0x41c00000
	s_mov_b32 s22, 0x41d00000
	s_mov_b32 s24, 0x42000000
	s_mov_b32 s26, 0x42080000
	v_lshlrev_b32_e32 v251, 2, v2
	v_or_b32_e32 v2, v0, v38
	v_or_b32_e32 v0, v0, v40
	s_mov_b32 s93, 0x42800000
	s_mov_b32 s14, 0
	s_movk_i32 s97, 0xc00
	v_mov_b32_e32 v165, v1
	v_mov_b32_e32 v167, v1
	v_mov_b32_e32 v169, v1
	v_mov_b32_e32 v171, v1
	v_mov_b32_e32 v173, v1
	v_mov_b32_e32 v175, v1
	v_mov_b32_e32 v177, v1
	s_mov_b32 s92, 0xf149f2ca
	s_mov_b32 s13, 0x41300000
	s_mov_b32 s17, 0x41880000
	s_mov_b32 s19, 0x41980000
	s_mov_b32 s21, 0x41c80000
	s_mov_b32 s23, 0x41d80000
	s_mov_b32 s25, 0x42040000
	s_mov_b32 s27, 0x420c0000
	s_mov_b32 s49, 0xc2800000
	v_add_u32_e32 v221, v210, v3
	v_add_u32_e32 v222, v210, v13
	v_add_u32_e32 v223, v210, v14
	v_add_u32_e32 v224, v210, v15
	v_add_u32_e32 v225, v210, v16
	v_add_u32_e32 v226, v210, v17
	v_add_u32_e32 v227, v210, v18
	v_add_u32_e32 v228, v210, v19
	v_add_u32_e32 v229, v210, v20
	v_add_u32_e32 v230, v210, v21
	v_add_u32_e32 v231, v210, v22
	v_add_u32_e32 v232, v210, v23
	v_add_u32_e32 v233, v210, v24
	v_add_u32_e32 v235, v210, v4
	v_add_u32_e32 v236, v25, v27
	v_add_u32_e32 v237, v25, v29
	v_add_u32_e32 v238, v25, v31
	v_add_u32_e32 v239, v25, v33
	v_add_u32_e32 v240, v25, v35
	v_add_u32_e32 v241, v25, v37
	v_add_u32_e32 v242, v25, v39
	v_add_u32_e32 v243, v25, v41
	v_mov_b32_e32 v244, 0xfff
	v_mov_b32_e32 v245, 0xf149f2ca
	v_lshlrev_b32_e32 v252, 2, v2
	v_lshlrev_b32_e32 v253, 2, v0
	v_mov_b32_e32 v214, 0
	s_mov_b64 s[44:45], s[54:55]
	s_mov_b64 s[42:43], s[6:7]
	s_mov_b64 s[40:41], s[4:5]
	s_mov_b64 s[36:37], s[56:57]
	s_mov_b64 s[34:35], s[58:59]
	s_mov_b64 s[30:31], s[70:71]
	s_mov_b64 s[28:29], s[60:61]
	s_branch .LBB0_474

;     __device__ __forceinline__ bool next(int i, Unit& o) const { if (i) return false; o = u; return true; }
;     __host__ __device__ bool next(int i, Unit& u) const {
;         const long L = (long)i * G + c; if (L >= nwg) return false;
;         int wgid = (int)L; { const int q = nwg / NXCD, r = nwg % NXCD, xcd = wgid % NXCD, off = wgid / NXCD; wgid = (xcd < r ? xcd * (q + 1) : r * (q + 1) + (xcd - r) * q) + off; }
;         const int nig = wgm * nN, gid = wgid / nig, fm = gid * wgm, gsz = (nM - fm) < wgm ? (nM - fm) : wgm;
;         u.pm = fm + ((wgid % nig) % gsz); u.pn = (wgid % nig) / gsz; return true;
; __device__ __forceinline__ void xcd_barrier(const XcdBarrier& b, const int wave) {
;     ...
;         }
;     }
;     __syncthreads();
.LBB0_598:
	s_cmp_eq_u32 s48, 64
	s_cbranch_scc0 mk_winv_p3
	s_cmp_eq_u32 s50, 0
	s_cbranch_scc0 mk_winv_p3
	buffer_inv sc1
	s_waitcnt vmcnt(0)
mk_winv_p3:
	s_mov_b32 s0, -1
	s_waitcnt lgkmcnt(0)
	s_barrier
	s_cmpk_lt_i32 s2, 0x200
	v_mbcnt_lo_u32_b32 v0, s0, 0
	v_mbcnt_hi_u32_b32 v8, s0, v0
	s_cselect_b64 s[0:1], -1, 0
	s_cmpk_gt_i32 s2, 0x1ff
	s_cbranch_scc1 .LBB0_604
	s_ashr_i32 s4, s2, 31
	s_lshr_b32 s4, s4, 29
	s_add_i32 s6, s2, s4
	s_and_b32 s4, s6, -8
	s_sub_i32 s7, s2, s4
	s_cmp_gt_i32 s7, -1
	s_cbranch_scc0 .LBB0_601
	s_lshl_b32 s8, s7, 6
	s_cbranch_execz .LBB0_602
	s_branch .LBB0_603

; __device__ __forceinline__ unsigned lane_id_fresh() { unsigned m = ~0u; asm volatile("" : "+s"(m)); return __builtin_amdgcn_mbcnt_hi(m, __builtin_amdgcn_mbcnt_lo(m, 0u)); }
; __device__ __forceinline__ void xcd_barrier_complete(unsigned* bar, unsigned x, unsigned& nloc, unsigned& nx) {
;     const unsigned G = gridDim.x * gridDim.y * gridDim.z;
;     unsigned sum, cnt, mine, sp = 0u;
;     for (;;) {
;         sum = 0u; cnt = 0u; mine = 0u;
; #pragma unroll
;         for (unsigned j = 0; j < 16; ++j) { const unsigned c = xb_ld(&bar[XB_XCNT(j)]); sum += c; cnt += (c > 0u) ? 1u : 0u; mine = (j == x) ? c : mine; }
;         if (sum == G) break;
;         __builtin_amdgcn_s_sleep(1);
;         if ((++sp & 255u) == 0u) { if (xb_ld(&bar[XB_TMO])) break; if (sp > XB_SPIN_CAP) { atomicAdd(&bar[XB_TMO], 1u); break; } }
;     }
;     nloc = mine > 0u ? mine : 1u; nx = cnt > 0u ? cnt : 1u;
; }
; __device__ __forceinline__ void xcd_barrier(const XcdBarrier& b, const int wave) {
;     asm volatile("s_waitcnt vmcnt(0)" ::: "memory");
;     __syncthreads();
;     if (wave == 0 && lane_id_fresh() == 0u) {
;         unsigned* bar = b.bar;
;         __builtin_amdgcn_s_waitcnt(0);
;         unsigned nloc = b.st[0], nx = b.st[1];
;         if (nloc == 0u) { xcd_barrier_complete(bar, b.x, nloc, nx); b.st[0] = nloc; b.st[1] = nx; }
;         const unsigned old = xb_add(&bar[XB_XSUB(b.x)], 1u);
;         const unsigned gen = old / nloc;
;         if (old + 1u == (gen + 1u) * nloc) {
;             __builtin_amdgcn_fence(__ATOMIC_RELEASE, "agent");
;             asm volatile("s_waitcnt vmcnt(0)" ::: "memory");
;             const unsigned og = xb_add(&bar[XB_TOP], 1u);
;             const unsigned tg = og / nx;
;             if (og + 1u == (tg + 1u) * nx) xb_add(&bar[XB_TOPGEN], 1u);
;             else XB_SPIN(xb_ld(&bar[XB_TOPGEN]) == tg, bar);
;             __builtin_amdgcn_fence(__ATOMIC_ACQUIRE, "agent");
;             xb_add(&bar[XB_XGEN(b.x)], 1u);
;             asm volatile("s_waitcnt vmcnt(0)" ::: "memory");
;         } else {
;             XB_SPIN(xb_ld(&bar[XB_XGEN(b.x)]) == gen, bar);
;             __builtin_amdgcn_fence(__ATOMIC_ACQUIRE, "agent");
;             asm volatile("s_waitcnt vmcnt(0)" ::: "memory");
;         }
;     }
;     __syncthreads();
; }
.LBB0_700:
	s_cmp_eq_u32 s48, 64
	s_cbranch_scc0 mk_winv_p4
	s_cmp_eq_u32 s50, 0
	s_cbranch_scc0 mk_winv_p4
	buffer_inv sc1
	s_waitcnt vmcnt(0)
mk_winv_p4:
	v_writelane_b32 v254, s66, 36
	s_add_u32 s0, s94, 0x60000
	s_mov_b32 s70, -1
	v_writelane_b32 v254, s67, 37
	v_writelane_b32 v254, s0, 38
	s_addc_u32 s0, s95, 0
	s_cmpk_gt_i32 s3, 0xff
	v_writelane_b32 v254, s0, 39
	s_cselect_b64 s[0:1], -1, 0
	v_writelane_b32 v254, s0, 40
	s_cmpk_lt_i32 s3, 0x100
	v_mov_b32_e32 v193, 0
	v_writelane_b32 v254, s1, 41
	s_cselect_b64 s[0:1], -1, 0
	v_writelane_b32 v254, s0, 42
	s_ashr_i32 s51, s2, 31
	v_mov_b32_e32 v227, 0x358637bd
	v_writelane_b32 v254, s1, 43
	s_lshr_b32 s0, s51, 29
	s_add_i32 s0, s2, s0
	s_ashr_i32 s20, s0, 3
	s_and_b32 s0, s0, -8
	s_sub_i32 s0, s2, s0
	s_lshl_b32 s1, s0, 7
	v_readlane_b32 s4, v254, 16
	s_cmp_eq_u32 s4, 1
	v_readlane_b32 s4, v254, 14
	s_cselect_b64 s[24:25], -1, 0
	s_cmpk_lt_u32 s4, 0x100
	s_cselect_b64 s[82:83], -1, 0
	s_ashr_i32 s49, s3, 31
	s_add_u32 s84, s94, 0x4200
	s_addc_u32 s85, s95, 0
	s_add_u32 s44, s94, 0x4400
	s_addc_u32 s45, s95, 0
	s_add_u32 s46, s94, 0x4500
	s_addc_u32 s47, s95, 0
	s_add_u32 s52, s94, 0x4600
	s_addc_u32 s53, s95, 0
	s_add_u32 s54, s94, 0x4700
	s_addc_u32 s55, s95, 0
	s_add_u32 s28, s94, 0x4800
	s_addc_u32 s29, s95, 0
	s_add_u32 s96, s94, 0x4900
	s_addc_u32 s97, s95, 0
	s_add_u32 s60, s94, 0x4a00
	s_addc_u32 s61, s95, 0
	s_add_u32 s58, s94, 0x4b00
	s_addc_u32 s59, s95, 0
	s_add_u32 s4, s94, 0x4c00
	s_addc_u32 s5, s95, 0
	s_add_u32 s6, s94, 0x4d00
	s_addc_u32 s7, s95, 0
	s_add_u32 s8, s94, 0x4e00
	s_addc_u32 s9, s95, 0
	s_add_u32 s10, s94, 0x4f00
	s_addc_u32 s11, s95, 0
	s_add_u32 s12, s94, 0x5000
	s_addc_u32 s13, s95, 0
	s_add_u32 s14, s94, 0x5100
	s_addc_u32 s15, s95, 0
	s_add_u32 s16, s94, 0x5200
	s_addc_u32 s17, s95, 0
	s_add_u32 s18, s94, 0x5300
	s_addc_u32 s19, s95, 0
	v_readlane_b32 s21, v254, 6
	s_cmp_eq_u32 s21, 15
	s_cselect_b64 s[22:23], -1, 0
	v_writelane_b32 v254, s22, 44
	s_cmp_eq_u32 s21, 14
	v_mov_b32_e32 v228, 1
	v_writelane_b32 v254, s23, 45
	s_cselect_b64 s[22:23], -1, 0
	v_writelane_b32 v254, s22, 46
	s_cmp_eq_u32 s21, 13
	s_movk_i32 s71, 0x1fff
	v_writelane_b32 v254, s23, 47
	s_cselect_b64 s[22:23], -1, 0
	v_writelane_b32 v254, s22, 48
	s_cmp_eq_u32 s21, 12
	v_mov_b64_e32 v[194:195], 0x400
	v_writelane_b32 v254, s23, 49
	s_cselect_b64 s[22:23], -1, 0
	v_writelane_b32 v254, s22, 50
	s_cmp_eq_u32 s21, 11
	v_mov_b64_e32 v[196:197], 0x3ff
	v_writelane_b32 v254, s23, 51
	s_cselect_b64 s[22:23], -1, 0
	v_writelane_b32 v254, s22, 52
	s_cmp_eq_u32 s21, 10
	v_mov_b64_e32 v[198:199], 0x100
	v_writelane_b32 v254, s23, 53
	s_cselect_b64 s[22:23], -1, 0
	v_writelane_b32 v254, s22, 54
	s_cmp_eq_u32 s21, 9
	v_mov_b64_e32 v[200:201], 0xff
	v_writelane_b32 v254, s23, 55
	s_cselect_b64 s[22:23], -1, 0
	v_writelane_b32 v254, s22, 56
	s_cmp_eq_u32 s21, 8
	v_mbcnt_hi_u32_b32 v229, -1, v253
	v_writelane_b32 v254, s23, 57
	s_cselect_b64 s[22:23], -1, 0
	v_writelane_b32 v254, s22, 58
	s_cmp_eq_u32 s21, 7
	s_mov_b32 s72, 0x46800000
	v_writelane_b32 v254, s23, 59
	s_cselect_b64 s[22:23], -1, 0
	v_writelane_b32 v254, s22, 60
	s_cmp_eq_u32 s21, 6
	s_mov_b64 s[78:79], 0
	v_writelane_b32 v254, s23, 61
	s_cselect_b64 s[22:23], -1, 0
	v_writelane_b32 v254, s22, 62
	s_cmp_eq_u32 s21, 5
	s_waitcnt lgkmcnt(0)
	v_writelane_b32 v254, s23, 63
	s_cselect_b64 s[22:23], -1, 0
	v_writelane_b32 v255, s22, 0
	s_cmp_eq_u32 s21, 4
	s_barrier
;     __device__ __forceinline__ bool next(int i, Unit& o) const { if (i) return false; o = u; return true; }
;     __host__ __device__ bool next(int i, Unit& u) const {
;         const long L = (long)i * G + c; if (L >= nwg) return false;
;         int wgid = (int)L; { const int q = nwg / NXCD, r = nwg % NXCD, xcd = wgid % NXCD, off = wgid / NXCD; wgid = (xcd < r ? xcd * (q + 1) : r * (q + 1) + (xcd - r) * q) + off; }
;         const int nig = wgm * nN, gid = wgid / nig, fm = gid * wgm, gsz = (nM - fm) < wgm ? (nM - fm) : wgm;
;         u.pm = fm + ((wgid % nig) % gsz); u.pn = (wgid % nig) / gsz; return true;
;     }
; __global__ void __launch_bounds__(NWAVES * 64, 2) mk_fwd(Args args) {
;     ...
;     const bool fuse7 = G >= (T / 2 / 256) * (DM / 256);
;     for (int half = 0; half < 2; ++half) {
;         const size_t roff = (size_t)half * (T / 2);
;         bf16_t* const ab = (fuse7 && half) ? (bf16_t*)(ws + WS_XB) : abuf;
;         {
;             pg8::AddrStd g{h1b + roff * DM, wup, 2048, 2048, 30, 0u}; pg8::StaticOrder S; S.init(T / 2, DFF, G, (int)blockIdx.x, WGM_U);
;             pg8::EpiB<2, 2, false> E{ab, DFF, ssq1 + roff, nullptr, 0, 0, 1.f};
;             pg8::gemm_phase<pg8::EpiB<2, 2, false>, pg8::StaticOrder, pg8::AddrStd, true>(lds, 2048, g, S, E, wave);
;         }
;         xcd_barrier(bar, wave);
;         if (fuse7) {
;             pg8::AddrStd g{ab, wd, DFF, DFF, 30, 0u}; pg8::StaticOrder S; S.init(T / 2, 2048, G, (int)blockIdx.x, WGM_D);
;             pg8::EpiResOut E{h1b + roff * DM, (unsigned long long*)(ws + WS_SSQX) + roff, out + roff * DM, g_fin, (unsigned*)(ws + WS_CTL) + CW_BAR + XB_TMO, 2048, 32u};
;             pg8::gemm_phase<pg8::EpiResOut, pg8::StaticOrder, pg8::AddrStd, true>(lds, DFF, g, S, E, wave);
	v_writelane_b32 v255, s23, 1
	s_cselect_b64 s[22:23], -1, 0
	v_writelane_b32 v255, s22, 2
	s_cmp_eq_u32 s21, 3
	s_nop 0
	v_writelane_b32 v255, s23, 3
	s_cselect_b64 s[22:23], -1, 0
	v_writelane_b32 v255, s22, 4
	s_cmp_eq_u32 s21, 2
	s_nop 0
	v_writelane_b32 v255, s23, 5
	s_cselect_b64 s[22:23], -1, 0
	v_writelane_b32 v255, s22, 6
	s_cmp_eq_u32 s21, 1
	s_nop 0
	v_writelane_b32 v255, s23, 7
	s_cselect_b64 s[22:23], -1, 0
	v_writelane_b32 v255, s22, 8
	s_cmp_eq_u32 s21, 0
	s_nop 0
	v_writelane_b32 v255, s23, 9
	s_cselect_b64 s[22:23], -1, 0
	s_lshl_b32 s21, s21, 8
	v_writelane_b32 v255, s22, 10
	s_add_u32 s21, s88, s21
	s_nop 0
	v_writelane_b32 v255, s23, 11
	s_addc_u32 s22, s89, 0
	s_add_u32 s26, s21, 0x1400
	s_addc_u32 s27, s22, 0
	v_writelane_b32 v255, s26, 12
	s_nop 1
	v_writelane_b32 v255, s27, 13
	s_add_u32 s26, s94, 0x7400
	s_addc_u32 s27, s95, 0
	s_add_u32 s22, s94, 0x7400
	s_addc_u32 s23, s95, 0
	v_writelane_b32 v255, s22, 14
	v_writelane_b32 v254, s26, 32
	s_nop 0
	v_writelane_b32 v255, s23, 15
	s_add_u32 s22, s94, 0x7400
	v_writelane_b32 v254, s27, 33
	s_addc_u32 s23, s95, 0
	v_writelane_b32 v254, s22, 14
	s_lshl_b32 s21, s0, 5
	s_nop 0
	v_writelane_b32 v254, s23, 15
	s_add_u32 s22, s94, 0x80000
	v_writelane_b32 v255, s22, 16
	s_addc_u32 s22, s95, 0
	v_writelane_b32 v255, s22, 17
	s_cmp_lt_i32 s0, 0
	s_mul_i32 s22, s0, 0x81
	s_cselect_b32 s1, s22, s1
	s_mul_i32 s0, s0, 33
	s_cselect_b32 s21, s0, s21
	s_add_i32 s0, s1, s20
	s_ashr_i32 s1, s0, 31
	s_lshr_b32 s1, s1, 25
	s_add_i32 s1, s0, s1
	s_and_b32 s22, s1, 0xff80
	s_sub_i32 s0, s0, s22
	s_bfe_i32 s22, s0, 0x80000
	s_bfe_u32 s22, s22, 0x2000d
	s_add_i32 s22, s0, s22
	s_and_b32 s23, s22, 0xfc
	s_sub_i32 s0, s0, s23
	s_ashr_i32 s1, s1, 7
	s_bfe_i32 s22, s22, 0x80000
	s_lshl_b32 s1, s1, 2
	s_sext_i32_i16 s22, s22
	s_sext_i32_i8 s0, s0
	s_add_i32 s26, s1, s0
	s_ashr_i32 s0, s22, 2
	v_writelane_b32 v255, s0, 18
	s_lshr_b32 s0, s22, 2
	s_mov_b32 s22, s26
	s_ashr_i32 s27, s26, 31
	s_bfe_i64 s[0:1], s[0:1], 0x100000
	v_writelane_b32 v255, s22, 19
	s_lshl_b64 s[0:1], s[0:1], 20
	v_writelane_b32 v254, s24, 26
	v_writelane_b32 v255, s23, 20
	s_lshl_b64 s[22:23], s[26:27], 20
	s_add_u32 s0, s64, s0
	v_writelane_b32 v255, s22, 21
	s_addc_u32 s1, s65, s1
	v_writelane_b32 v254, s25, 27
	v_writelane_b32 v255, s23, 22
	s_add_u32 s22, s0, 0x80000
	s_addc_u32 s23, s1, 0
	v_writelane_b32 v255, s22, 23
	v_cndmask_b32_e64 v226, 0, 1, s[24:25]
	s_nop 0
	v_writelane_b32 v255, s23, 24
	s_add_u32 s22, s0, 0x80080
	v_writelane_b32 v255, s0, 25
	s_addc_u32 s23, s1, 0
	s_nop 0
	v_writelane_b32 v255, s1, 26
	s_add_i32 s0, s21, s20
	s_ashr_i32 s1, s0, 31
	s_lshr_b32 s1, s1, 27
	s_add_i32 s1, s0, s1
	s_and_b32 s20, s1, 0xffe0
	s_sub_i32 s0, s0, s20
	s_bfe_i32 s20, s0, 0x80000
	s_bfe_u32 s20, s20, 0x2000d
	s_add_i32 s20, s0, s20
	s_and_b32 s21, s20, 0xfc
	s_sub_i32 s0, s0, s21
	s_ashr_i32 s1, s1, 5
	s_bfe_i32 s20, s20, 0x80000
	v_writelane_b32 v255, s22, 27
	s_lshl_b32 s1, s1, 2
	s_sext_i32_i16 s20, s20
	s_sext_i32_i8 s0, s0
	v_writelane_b32 v255, s23, 28
	s_add_i32 s22, s1, s0
	s_ashr_i32 s0, s20, 2
	v_writelane_b32 v255, s0, 29
	s_lshr_b32 s0, s20, 2
	s_mov_b32 s20, s22
	s_ashr_i32 s23, s22, 31
	s_bfe_i64 s[0:1], s[0:1], 0x100000
	v_writelane_b32 v255, s20, 30
	s_lshl_b64 s[0:1], s[0:1], 22
	s_nop 0
	v_writelane_b32 v255, s21, 31
	s_lshl_b64 s[20:21], s[22:23], 22
	s_add_u32 s0, s62, s0
	s_addc_u32 s1, s63, s1
	s_add_u32 s22, s0, 0x200000
	s_addc_u32 s23, s1, 0
	v_writelane_b32 v255, s22, 32
	s_nop 1
	v_writelane_b32 v255, s23, 33
	s_add_u32 s22, s68, s20
	v_writelane_b32 v255, s20, 34
	s_addc_u32 s23, s69, s21
	s_nop 0
	v_writelane_b32 v255, s21, 35
	s_add_u32 s20, s22, 0x200000
	v_writelane_b32 v255, s22, 36
	s_addc_u32 s21, s23, 0
	s_nop 0
	v_writelane_b32 v255, s23, 37
	v_writelane_b32 v255, s20, 38
	s_nop 1
	v_writelane_b32 v255, s21, 39
	s_add_u32 s20, s0, 0x200080
	v_writelane_b32 v255, s0, 40
	s_addc_u32 s21, s1, 0
	s_nop 0
	v_writelane_b32 v255, s1, 41
	v_writelane_b32 v255, s20, 42
	s_add_i32 s0, 0, 0x20160
	s_nop 0
	v_writelane_b32 v255, s21, 43
	v_writelane_b32 v255, s0, 44
	s_add_i32 s0, 0, 0x20164
	v_writelane_b32 v255, s0, 45
	v_writelane_b32 v255, s44, 46
	s_mov_b64 s[0:1], -1
	v_writelane_b32 v254, s0, 10
	v_writelane_b32 v255, s45, 47
	v_writelane_b32 v255, s46, 48
	v_writelane_b32 v254, s1, 11
	s_mov_b64 s[20:21], 0
	v_writelane_b32 v255, s47, 49
	v_readlane_b32 s95, v254, 18
	v_writelane_b32 v254, s74, 6
	v_writelane_b32 v255, s52, 50
	s_nop 0
	v_writelane_b32 v254, s75, 7
	v_writelane_b32 v255, s53, 51
	v_writelane_b32 v255, s54, 52
	v_writelane_b32 v254, s28, 16
	s_nop 0
	v_writelane_b32 v255, s55, 53
	v_writelane_b32 v254, s29, 17
	s_branch .LBB0_703

;     __device__ __forceinline__ unsigned voffA(int R, int C) const { return (unsigned)(R * lda + C) * 2u; }
;     __device__ __forceinline__ unsigned voffB(int R, int C) const { return (unsigned)(R * ldb + C) * 2u; }
;     __device__ __forceinline__ size_t hA() const { return (size_t)HALF * lda * 2; }
;     __device__ __forceinline__ size_t hB() const { return (size_t)HALF * ldb * 2; }
;     __device__ __forceinline__ const char* a(const Unit& u) const { return (const char*)A + (size_t)u.pm * 2 * hA(); }
;     __device__ __forceinline__ const char* b(const Unit& u) const { return (const char*)Bt + (size_t)u.pn * 2 * hB() + (size_t)(u.pm >> gshift) * goff; }
;     __device__ __forceinline__ unsigned voffA(int R, int C) const { return (unsigned)(R * 256 + C) * 2u; }
;     __device__ __forceinline__ unsigned voffB(int R, int C) const { return (unsigned)((256 * (R & 15) + (R >> 4)) * 1024 + C) * 2u; }
;     __device__ __forceinline__ size_t hA() const { return (size_t)HALF * 256 * 2; }
;     __device__ __forceinline__ size_t hB() const { return (size_t)8 * 1024 * 2; }
;     __device__ __forceinline__ const char* a(const Unit& u) const { return (const char*)A + (size_t)u.pm * 2 * hA(); }
; #define PG8_BAR __builtin_amdgcn_s_barrier()
;     ...
;     for (int i = 0; i < 2; ++i) { int R, C; stage_rc(tid * 16 + i * 8192, R, C); const int Rb = Epi::PERM ? ((R & ~31) + perm32(R & 31)) : R;
;         voffA[i] = g.voffA(R, C); voffB[i] = g.voffB(Rb, C); }
;     const size_t kstep = (size_t)(BK * 2);
;     const size_t hstepA = g.hA(), hstepB = g.hB();
;     const unsigned ldsw = (unsigned)wid * 1024u;
;     const int aoff = lds_byte(wr * 64 + fr, fq * 8), boff = lds_byte(wc * 32 + fr, fq * 8);
;     ...
;     Unit cur, nxt; int ui = 0;
;     if (!S.next(0, cur)) return;
;     f32x4 acc[2][2][4][2];
; #pragma unroll
;     for (int a = 0; a < 2; ++a)
; #pragma unroll
;         for (int b = 0; b < 2; ++b)
; #pragma unroll
;             for (int m = 0; m < 4; ++m)
; #pragma unroll
;                 for (int n = 0; n < 2; ++n) acc[a][b][m][n] = (f32x4){0.f, 0.f, 0.f, 0.f};
;     bf16x8 At[4][2], B0[2][2], B1[2][2];
;     const char* cA = g.a(cur); const char* cB = g.b(cur);
;     S.a_ready(cur);
;     PG8_STAGE(PG8_SB(0, 0), cB, voffB); PG8_STAGE(PG8_SB(0, 1), cB + hstepB, voffB); PG8_STAGE(PG8_SA(0, 0), cA, voffA); PG8_STAGE(PG8_SA(0, 1), cA + hstepA, voffA);
;     if (wr == 1) PG8_BAR;
.LBB0_777:
	s_cmp_eq_u32 s48, 64
	s_cbranch_scc0 mk_winv_p5
	s_cmp_eq_u32 s50, 0
	s_cbranch_scc0 mk_winv_p5
	buffer_inv sc1
	s_waitcnt vmcnt(0)
mk_winv_p5:
	v_readlane_b32 s0, v254, 42
	v_readlane_b32 s1, v254, 43
	s_and_b64 vcc, exec, s[0:1]
	v_readlane_b32 s0, v254, 34
	v_readlane_b32 s1, v254, 35
	s_mov_b64 s[20:21], -1
	s_waitcnt lgkmcnt(0)
	v_cndmask_b32_e64 v0, 0, 1, s[0:1]
	v_cmp_ne_u32_e64 s[38:39], 1, v0
	s_barrier
	s_cbranch_vccz .LBB0_869
	s_mov_b32 s0, s70
	s_and_b64 vcc, exec, s[38:39]
	v_mbcnt_lo_u32_b32 v0, s0, 0
	v_mbcnt_hi_u32_b32 v0, s0, v0
	s_cbranch_vccnz .LBB0_814
	v_lshl_add_u32 v1, v0, 4, s33
	v_ashrrev_i32_e32 v2, 31, v1
	v_lshrrev_b32_e32 v2, 22, v2
	v_add_u32_e32 v2, v1, v2
	v_ashrrev_i32_e32 v2, 10, v2
	v_mul_i32_i24_e32 v3, 0x400, v2
	v_sub_u32_e32 v3, v1, v3
	v_lshrrev_b32_e32 v4, 4, v3
	v_bitop3_b32 v3, v4, v3, 32 bitop3:0x6c
	v_ashrrev_i32_e32 v5, 31, v3
	v_lshrrev_b32_e32 v5, 26, v5
	v_lshlrev_b32_e32 v4, 3, v2
	v_add_u32_e32 v5, v3, v5
	v_and_b32_e32 v4, -16, v4
	v_ashrrev_i32_e32 v6, 6, v5
	v_and_b32_e32 v5, 0xc0, v5
	v_add_u32_e32 v4, v6, v4
	v_sub_u32_e32 v3, v3, v5
	v_lshlrev_b32_e32 v2, 5, v2
	v_ashrrev_i16_sdwa v3, v228, sext(v3) dst_sel:DWORD dst_unused:UNUSED_PAD src0_sel:DWORD src1_sel:BYTE_0
	v_lshlrev_b32_e32 v5, 1, v4
	v_lshrrev_b32_e32 v7, 2, v4
	v_and_b32_e32 v6, 3, v6
	s_mov_b32 s0, 0x3ffe0
	v_and_b32_e32 v2, 32, v2
	v_bfe_i32 v3, v3, 0, 16
	v_and_b32_e32 v5, 24, v5
	v_and_b32_e32 v7, 4, v7
	v_and_or_b32 v6, v4, s0, v6
	v_or3_b32 v5, v6, v7, v5
	v_add_lshl_u32 v2, v2, v3, 1
	v_add_u32_e32 v1, 0x2000, v1
	v_lshl_add_u32 v188, v4, 14, v2
	v_lshl_add_u32 v192, v5, 14, v2
	v_ashrrev_i32_e32 v2, 31, v1
	v_lshrrev_b32_e32 v2, 22, v2
	v_add_u32_e32 v2, v1, v2
	v_ashrrev_i32_e32 v2, 10, v2
	v_mul_i32_i24_e32 v3, 0x400, v2
	v_sub_u32_e32 v1, v1, v3
	v_lshrrev_b32_e32 v3, 4, v1
	v_bitop3_b32 v1, v3, v1, 32 bitop3:0x6c
	v_ashrrev_i32_e32 v4, 31, v1
	v_lshrrev_b32_e32 v4, 26, v4
	v_add_u32_e32 v4, v1, v4
	v_ashrrev_i32_e32 v5, 6, v4
	v_and_b32_e32 v4, 0xffc0, v4
	v_sub_u32_e32 v1, v1, v4
	v_lshlrev_b32_e32 v3, 3, v2
	v_lshrrev_b16_e32 v4, 7, v1
	v_and_b32_e32 v3, -16, v3
	v_and_b32_e32 v4, 1, v4
	v_add_u32_e32 v3, v5, v3
	v_add_u16_e32 v1, v1, v4
	v_lshlrev_b32_e32 v2, 5, v2
	v_ashrrev_i16_sdwa v1, v228, sext(v1) dst_sel:DWORD dst_unused:UNUSED_PAD src0_sel:DWORD src1_sel:BYTE_0
	v_lshlrev_b32_e32 v4, 1, v3
	v_lshrrev_b32_e32 v6, 2, v3
	v_and_b32_e32 v5, 3, v5
	v_and_b32_e32 v2, 32, v2
	v_bfe_i32 v1, v1, 0, 16
	v_and_b32_e32 v4, 24, v4
	v_and_b32_e32 v6, 4, v6
	v_and_or_b32 v5, v3, s0, v5
	s_add_i32 s0, s33, 0
	v_readlane_b32 s20, v255, 40
	v_or3_b32 v4, v5, v6, v4
	v_add_lshl_u32 v1, v2, v1, 1
	s_add_i32 m0, s0, 0x10000
	v_readlane_b32 s21, v255, 41
	v_lshl_add_u32 v202, v4, 14, v1
	s_add_i32 s1, s0, 0x2000
	v_lshl_add_u32 v190, v3, 14, v1
	s_add_i32 s34, s0, 0x4000
	s_add_i32 s35, s0, 0x6000
	global_load_lds_dwordx4 v192, s[20:21]
	s_add_i32 m0, s0, 0x12000
	v_cmp_ne_u32_e64 s[40:41], 1, v226
	global_load_lds_dwordx4 v202, s[20:21]
	v_readlane_b32 s20, v255, 32
	s_add_i32 m0, s0, 0x14000
	v_readlane_b32 s21, v255, 33
	s_nop 4
	global_load_lds_dwordx4 v192, s[20:21]
	s_add_i32 m0, s0, 0x16000
	s_nop 0
	global_load_lds_dwordx4 v202, s[20:21]
	v_readlane_b32 s20, v255, 36
	s_mov_b32 m0, s0
	v_readlane_b32 s21, v255, 37
	s_nop 4
	global_load_lds_dwordx4 v188, s[20:21]
	s_mov_b32 m0, s1
	s_nop 0
	global_load_lds_dwordx4 v190, s[20:21]
	v_readlane_b32 s20, v255, 38
	s_mov_b32 m0, s34
	v_readlane_b32 s21, v255, 39
	s_nop 4
	global_load_lds_dwordx4 v188, s[20:21]
	s_mov_b32 m0, s35
	s_nop 0
	global_load_lds_dwordx4 v190, s[20:21]
	v_readlane_b32 s20, v254, 26
	v_readlane_b32 s21, v254, 27
	s_andn2_b64 vcc, exec, s[20:21]
	s_cbranch_vccnz .LBB0_781
	s_barrier
